# rope half of Q kept resident in VGPRs for the prompt attention item (no per-tile LDS reads), 6-deep LDS rings
# speedup vs baseline: 1.0085x; 1.0042x over previous
;     ...
;   int tid_ = threadIdx.x;
;   asm volatile("" : "+v"(tid_));
;   const int tid = tid_, lane = tid & 63, w = tid >> 6, h = lane >> 5, r = lane & 31;
;   constexpr int NQR = (NQF > 8) ? 8 : NQF;
;   bf16x8 qf[NQR];
;   const u16* qp = Qb + (long)(w * 32 + r) * ldq + h * 8;
;   if (nkt_w > 0) {
; #pragma unroll
;     for (int ks = 0; ks < NQR; ks++) qf[ks] = *(const bf16x8*)(qp + ks * 16);
;   } else {
; #pragma unroll
;     for (int ks = 0; ks < NQR; ks++) qf[ks] = (bf16x8){0, 0, 0, 0, 0, 0, 0, 0};
;   }
;   u16* Qs = Vs + 128 * 68;
;   if (NQF > NQR) {
;     const int qrow = tid >> 1, qhalf = tid & 1;
;     const bool qvalid = (nkt_w > 0) || (qrow < 64);
;     const u16* qsrc = Qb + (long)qrow * ldq + NQR * 16 + qhalf * 32;
; #pragma unroll
;     for (int c = 0; c < 4; c++) {
;       uint4 v = make_uint4(0, 0, 0, 0);
;       if (qvalid) v = *(const uint4*)(qsrc + c * 8);
;       *(uint4*)(Qs + qrow * 72 + qhalf * 32 + c * 8) = v;
;     }
;   }
;   f32x16 o[4];
; #pragma unroll
;   for (int mc = 0; mc < 4; mc++)
; #pragma unroll
;     for (int i = 0; i < 16; i++) o[mc][i] = 0.f;
;   float m_run = -1e30f, l_run = 0.f;
;   uint4 rk0, rk1, rk2, rk3, rk4 = make_uint4(0, 0, 0, 0), rk5 = make_uint4(0, 0, 0, 0), rv0, rv1, rv2, rv3;
;   const unsigned voffK = (unsigned)(((tid >> 4) * (int)ldk1 + (tid & 15) * 8) * 2);
;   const unsigned voffR = (unsigned)(((tid >> 3) * (int)ldk2 + (tid & 7) * 8) * 2);
;   const unsigned voffV = (unsigned)(((tid >> 3) * (int)ldvt + (tid & 7) * 8) * 2);
;   u16* const ldsK = Ks + (tid >> 4) * KLD + (tid & 15) * 8;
;   u16* const ldsR = Ks + (tid >> 3) * KLD + (16 + (tid & 7)) * 8;
;   u16* const ldsV = Vs + (tid >> 3) * 68 + (tid & 7) * 8;
;     ...
;   ATT_GLOAD(rev ? nkt - 1 : 0);
; DI void attn_phase_l0(const Params& p, int g, unsigned* qcnt, char* smem) {
;     ...
;       const int qt = 127 - (it >> 3), hd = it & 7;
;       const int nkt = 2 * qt + 2, nkw = (w < 2) ? 2 * qt + 1 : 2 * qt + 2;
;       u16* qb = Q + (long)qt * 128 * 1536 + hd * 192;
;       attn_item<192>(qb, 1536, knp + (long)hd * NP * 128, 128, krall, 64, vtp + (long)hd * (NP / 64) * 8192, 64, nkt, nkw, qb, 1536, smem, qt < 64, 8192);
.LBB0_653:
	v_ashrrev_i32_e32 v37, 3, v3
	v_sub_u32_e32 v0, 0x7f, v37
	v_and_b32_e32 v4, 7, v3
	v_mov_b64_e32 v[2:3], s[38:39]
	s_mov_b32 s0, 0x60000
	v_lshlrev_b32_e32 v41, 1, v0
	v_mad_u64_u32 v[2:3], s[0:1], v0, s0, v[2:3]
	v_mul_u32_u24_e32 v0, 0xc0, v4
	v_lshlrev_b32_e32 v0, 1, v0
	v_mov_b32_e32 v51, v202
	v_lshl_add_u64 v[16:17], v[2:3], 0, v[0:1]
	v_lshlrev_b32_e32 v0, 22, v4
	v_lshl_add_u64 v[32:33], s[40:41], 0, v[0:1]
	v_ashrrev_i32_e32 v18, 1, v51
	s_waitcnt vmcnt(0)
	v_lshl_add_u64 v[172:173], s[42:43], 0, v[0:1]
	v_bfi_b32 v52, s86, v18, v51
	v_lshlrev_b32_e32 v0, 6, v51
	v_or_b32_e32 v50, 1, v41
	v_mad_i64_i32 v[186:187], s[0:1], v52, s85, v[16:17]
	v_mad_i64_i32 v[16:17], s[0:1], v18, s85, v[16:17]
	v_and_b32_e32 v0, 64, v0
	v_cmp_lt_i32_e64 s[8:9], 63, v37
	v_bfe_u32 v213, v51, 5, 1
	v_lshl_add_u64 v[28:29], v[16:17], 0, v[0:1]
	v_mad_u64_u32 v[34:35], s[0:1], v18, s82, v[0:1]
	v_lshlrev_b32_e32 v0, 4, v51
	v_cndmask_b32_e64 v42, 0, v50, s[8:9]
	v_lshlrev_b32_e32 v14, 4, v213
	v_mov_b32_e32 v15, v1
	v_and_b32_e32 v36, 0xf0, v0
	v_and_b32_e32 v40, 0x70, v0
	v_lshlrev_b32_e32 v0, 6, v42
	v_lshl_add_u64 v[2:3], v[186:187], 0, v[14:15]
	v_ashrrev_i32_e32 v15, 4, v51
	v_lshlrev_b64 v[44:45], 8, v[0:1]
	v_or_b32_e32 v46, 16, v0
	v_mov_b32_e32 v47, v1
	v_lshl_or_b32 v38, v15, 8, v36
	v_lshl_add_u64 v[44:45], v[32:33], 0, v[44:45]
	v_mov_b32_e32 v39, v1
	v_lshlrev_b64 v[46:47], 8, v[46:47]
	v_lshl_add_u64 v[44:45], v[44:45], 0, v[38:39]
	v_lshl_add_u64 v[46:47], v[32:33], 0, v[46:47]
	global_load_dwordx4 v[128:131], v[2:3], off
	global_load_dwordx4 v[124:127], v[2:3], off offset:32
	global_load_dwordx4 v[120:123], v[2:3], off offset:64
	global_load_dwordx4 v[116:119], v[2:3], off offset:96
	global_load_dwordx4 v[112:115], v[2:3], off offset:128
	global_load_dwordx4 v[10:13], v[2:3], off offset:160
	global_load_dwordx4 v[6:9], v[2:3], off offset:192
	s_nop 0
	global_load_dwordx4 v[214:217], v[2:3], off offset:256
	global_load_dwordx4 v[218:221], v[2:3], off offset:288
	global_load_dwordx4 v[222:225], v[2:3], off offset:320
	global_load_dwordx4 v[228:231], v[2:3], off offset:352
	global_load_dwordx4 v[2:5], v[2:3], off offset:224
	s_nop 0
	global_load_dwordx4 v[16:19], v[28:29], off offset:304
	global_load_dwordx4 v[20:23], v[28:29], off offset:288
	global_load_dwordx4 v[24:27], v[28:29], off offset:272
	s_nop 0
	global_load_dwordx4 v[28:31], v[28:29], off offset:256
	v_lshl_add_u64 v[46:47], v[46:47], 0, v[38:39]
	global_load_dwordx4 v[132:135], v[44:45], off
	global_load_dwordx4 v[136:139], v[46:47], off
	v_or_b32_e32 v44, 32, v0
	v_mov_b32_e32 v45, v1
	v_lshlrev_b64 v[46:47], 8, v[44:45]
	v_or_b32_e32 v48, 48, v0
	v_mov_b32_e32 v49, v1
	v_ashrrev_i32_e32 v35, 3, v51
	v_lshl_add_u64 v[46:47], v[32:33], 0, v[46:47]
	v_lshlrev_b64 v[48:49], 8, v[48:49]
	v_lshl_or_b32 v43, v35, 7, v40
	v_lshl_add_u64 v[46:47], v[46:47], 0, v[38:39]
	v_lshl_add_u64 v[48:49], v[32:33], 0, v[48:49]
	v_lshl_add_u64 v[48:49], v[48:49], 0, v[38:39]
	global_load_dwordx4 v[140:143], v[46:47], off
	global_load_dwordx4 v[144:147], v[48:49], off
	v_lshlrev_b64 v[46:47], 7, v[0:1]
	v_mov_b32_e32 v0, v43
	v_mov_b32_e32 v43, v1
	v_lshlrev_b64 v[44:45], 7, v[44:45]
	v_lshlrev_b64 v[42:43], 14, v[42:43]
	v_lshl_add_u64 v[46:47], s[76:77], 0, v[46:47]
	v_lshl_add_u64 v[44:45], s[76:77], 0, v[44:45]
	v_lshl_add_u64 v[42:43], v[172:173], 0, v[42:43]
	v_lshl_add_u64 v[46:47], v[46:47], 0, v[0:1]
	v_lshl_add_u64 v[44:45], v[44:45], 0, v[0:1]
	v_lshl_add_u64 v[42:43], v[42:43], 0, v[0:1]
	global_load_dwordx4 v[152:155], v[46:47], off
	global_load_dwordx4 v[148:151], v[44:45], off
	v_add_co_u32_e32 v44, vcc, s46, v42
	v_add_u32_e32 v41, 2, v41
	s_nop 0
	v_addc_co_u32_e32 v45, vcc, 0, v43, vcc
	global_load_dwordx4 v[156:159], v[44:45], off offset:-4096
	global_load_dwordx4 v[160:163], v[44:45], off
	v_add_co_u32_e32 v44, vcc, s47, v42
	v_cndmask_b32_e64 v188, v41, v50, s[6:7]
	s_nop 0
	v_addc_co_u32_e32 v45, vcc, 0, v43, vcc
	global_load_dwordx4 v[168:171], v[42:43], off
	global_load_dwordx4 v[164:167], v[44:45], off
	v_and_b32_e32 v41, 31, v51
	v_lshlrev_b32_e32 v42, 3, v213
	s_waitcnt vmcnt(10)
	ds_write_b128 v34, v[28:31] offset:43008
	ds_write_b128 v34, v[24:27] offset:43024
	ds_write_b128 v34, v[20:23] offset:43040
	ds_write_b128 v34, v[16:19] offset:43056
	v_mad_u64_u32 v[176:177], s[0:1], v15, s44, v[36:37]
	v_mad_u64_u32 v[174:175], s[0:1], v35, s44, v[40:41]
	v_mov_b32_e32 v30, v1
	v_mov_b32_e32 v31, v1
	v_mad_u64_u32 v[178:179], s[0:1], v35, s45, v[174:175]
	v_lshl_add_u64 v[180:181], v[32:33], 0, v[38:39]
	v_mul_lo_u32 v190, v52, s82
	v_sub_u32_e32 v175, v14, v42
	v_mul_u32_u24_e32 v189, 0x190, v41
	v_mul_u32_u24_e32 v177, 0x88, v41
	v_lshlrev_b32_e32 v15, 1, v37
	v_mov_b32_e32 v16, v1
	v_mov_b32_e32 v17, v1
	v_mov_b32_e32 v18, v1
	v_mov_b32_e32 v19, v1
	v_mov_b32_e32 v20, v1
	v_mov_b32_e32 v21, v1
	v_mov_b32_e32 v22, v1
	v_mov_b32_e32 v23, v1
	v_mov_b32_e32 v24, v1
	v_mov_b32_e32 v25, v1
	v_mov_b32_e32 v26, v1
	v_mov_b32_e32 v27, v1
	v_mov_b32_e32 v28, v1
	v_mov_b32_e32 v29, v1
	v_mov_b64_e32 v[46:47], v[30:31]
	v_mov_b64_e32 v[62:63], v[30:31]
	v_mov_b64_e32 v[78:79], v[30:31]
	s_mov_b32 s2, 0
	v_lshl_add_u64 v[182:183], s[76:77], 0, v[0:1]
	v_cndmask_b32_e64 v191, 1, -1, s[8:9]
	v_sub_u32_e32 v192, 0xff, v15
	v_mov_b32_e32 v179, 0xf149f2ca
	v_mov_b32_e32 v15, 0
	s_mov_b64 s[0:1], 0
	v_mov_b64_e32 v[44:45], v[28:29]
	v_mov_b64_e32 v[42:43], v[26:27]
	v_mov_b64_e32 v[40:41], v[24:25]
	v_mov_b64_e32 v[38:39], v[22:23]
	v_mov_b64_e32 v[36:37], v[20:21]
	v_mov_b64_e32 v[34:35], v[18:19]
	v_mov_b64_e32 v[32:33], v[16:17]
	v_mov_b64_e32 v[60:61], v[28:29]
	v_mov_b64_e32 v[58:59], v[26:27]
	v_mov_b64_e32 v[56:57], v[24:25]
	v_mov_b64_e32 v[54:55], v[22:23]
	v_mov_b64_e32 v[52:53], v[20:21]
	v_mov_b64_e32 v[50:51], v[18:19]
	v_mov_b64_e32 v[48:49], v[16:17]
	v_mov_b64_e32 v[76:77], v[28:29]
	v_mov_b64_e32 v[74:75], v[26:27]
	v_mov_b64_e32 v[72:73], v[24:25]
	v_mov_b64_e32 v[70:71], v[22:23]
	v_mov_b64_e32 v[68:69], v[20:21]
	v_mov_b64_e32 v[66:67], v[18:19]
	v_mov_b64_e32 v[64:65], v[16:17]
	s_branch .LBB0_656
; #define MFMA(a, b, c) __builtin_amdgcn_mfma_f32_32x32x16_bf16((a), (b), (c), 0, 0, 0)
; DI unsigned pack2(float a, float b) { f32v2_t v = {a, b}; return __builtin_bit_cast(unsigned, __builtin_convertvector(v, bf16v2_t)); }
;     ...
;       float sum = 0.f;
; #pragma unroll
;       for (int mt = 0; mt < 2; mt++)
; #pragma unroll
;         for (int i = 0; i < 16; i++) { const float e = __builtin_amdgcn_exp2f(s[mt][i] - m_run); s[mt][i] = e; sum += e; }
;       l_run += sum;
;       __builtin_amdgcn_s_setprio(1);
; #pragma unroll
;       for (int mt = 0; mt < 2; mt++) {
; #pragma unroll
;         for (int sp = 0; sp < 2; sp++) {
;           const int st = 2 * mt + sp;
;           unsigned pp[4];
; #pragma unroll
;           for (int j = 0; j < 4; j++) pp[j] = pack2(s[mt][8 * sp + 2 * j], s[mt][8 * sp + 2 * j + 1]);
;           const bf16x8 pf = __builtin_bit_cast(bf16x8, make_uint4(pp[0], pp[1], pp[2], pp[3]));
; #pragma unroll
;           for (int mc = 0; mc < 4; mc++) {
;             const u16* vp = Vs + (mc * 32 + r) * 68 + 16 * st + 4 * h;
;             const uint2 lo = *(const uint2*)vp;
;             const uint2 hi = *(const uint2*)(vp + 8);
;             const bf16x8 vf = __builtin_bit_cast(bf16x8, make_uint4(lo.x, lo.y, hi.x, hi.y));
;             o[mc] = MFMA(vf, pf, o[mc]);
;           }
;         }
;       }
;       __builtin_amdgcn_s_setprio(0);
.LBB0_654:
	v_sub_f32_e32 v96, v96, v179
	v_exp_f32_e32 v96, v96
	v_sub_f32_e32 v97, v97, v179
	v_sub_f32_e32 v98, v98, v179
	v_exp_f32_e32 v97, v97
	v_exp_f32_e32 v98, v98
	v_sub_f32_e32 v99, v99, v179
	v_exp_f32_e32 v99, v99
	v_sub_f32_e32 v100, v100, v179
	v_add_f32_e32 v197, 0, v96
	v_exp_f32_e32 v100, v100
	v_sub_f32_e32 v101, v101, v179
	v_add_f32_e32 v197, v97, v197
	v_exp_f32_e32 v101, v101
	v_sub_f32_e32 v102, v102, v179
	v_add_f32_e32 v197, v98, v197
	v_exp_f32_e32 v102, v102
	v_sub_f32_e32 v103, v103, v179
	v_add_f32_e32 v197, v99, v197
	v_exp_f32_e32 v103, v103
	v_sub_f32_e32 v104, v104, v179
	v_add_f32_e32 v197, v100, v197
	v_exp_f32_e32 v104, v104
	v_sub_f32_e32 v105, v105, v179
	v_add_f32_e32 v197, v101, v197
	v_exp_f32_e32 v105, v105
	v_sub_f32_e32 v106, v106, v179
	v_add_f32_e32 v197, v102, v197
	v_exp_f32_e32 v106, v106
	v_sub_f32_e32 v107, v107, v179
	v_add_f32_e32 v197, v103, v197
	v_exp_f32_e32 v107, v107
	v_sub_f32_e32 v108, v108, v179
	v_add_f32_e32 v197, v104, v197
	v_exp_f32_e32 v108, v108
	v_sub_f32_e32 v109, v109, v179
	v_add_f32_e32 v197, v105, v197
	v_exp_f32_e32 v109, v109
	v_sub_f32_e32 v110, v110, v179
	v_add_f32_e32 v197, v106, v197
	v_exp_f32_e32 v110, v110
	v_sub_f32_e32 v111, v111, v179
	v_sub_f32_e32 v80, v80, v179
	v_sub_f32_e32 v81, v81, v179
	v_sub_f32_e32 v82, v82, v179
	v_sub_f32_e32 v83, v83, v179
	v_sub_f32_e32 v84, v84, v179
	v_sub_f32_e32 v85, v85, v179
	v_sub_f32_e32 v86, v86, v179
	v_sub_f32_e32 v87, v87, v179
	v_sub_f32_e32 v88, v88, v179
	v_sub_f32_e32 v89, v89, v179
	v_sub_f32_e32 v90, v90, v179
	v_sub_f32_e32 v91, v91, v179
	v_sub_f32_e32 v92, v92, v179
	v_sub_f32_e32 v93, v93, v179
	v_sub_f32_e32 v94, v94, v179
	v_sub_f32_e32 v95, v95, v179
	v_add_f32_e32 v197, v107, v197
	v_exp_f32_e32 v111, v111
	v_exp_f32_e32 v80, v80
	v_exp_f32_e32 v81, v81
	v_exp_f32_e32 v82, v82
	v_exp_f32_e32 v83, v83
	v_exp_f32_e32 v84, v84
	v_exp_f32_e32 v85, v85
	v_exp_f32_e32 v86, v86
	v_exp_f32_e32 v87, v87
	v_exp_f32_e32 v88, v88
	v_exp_f32_e32 v89, v89
	v_exp_f32_e32 v90, v90
	v_exp_f32_e32 v91, v91
	v_exp_f32_e32 v92, v92
	v_exp_f32_e32 v93, v93
	v_exp_f32_e32 v94, v94
	v_exp_f32_e32 v95, v95
	v_add_f32_e32 v197, v108, v197
	v_add_f32_e32 v197, v109, v197
	v_add_f32_e32 v197, v110, v197
	v_add_f32_e32 v197, v111, v197
	s_setprio 1
	v_cvt_pk_bf16_f32 v96, v96, v97
	v_cvt_pk_bf16_f32 v97, v98, v99
	v_cvt_pk_bf16_f32 v98, v100, v101
	v_cvt_pk_bf16_f32 v99, v102, v103
	v_cvt_pk_bf16_f32 v100, v104, v105
	v_cvt_pk_bf16_f32 v101, v106, v107
	v_cvt_pk_bf16_f32 v102, v108, v109
	v_cvt_pk_bf16_f32 v103, v110, v111
	s_waitcnt lgkmcnt(10)
	v_mfma_f32_32x32x16_bf16 v[64:79], v[232:235], v[96:99], v[64:79]
	ds_read_b64 v[232:233], v227 offset:34336
	ds_read_b64 v[234:235], v227 offset:34352
	v_add_f32_e32 v197, v80, v197
	v_add_f32_e32 v197, v81, v197
	v_add_f32_e32 v197, v82, v197
	v_add_f32_e32 v197, v83, v197
	v_add_f32_e32 v197, v84, v197
	s_waitcnt lgkmcnt(10)
	v_mfma_f32_32x32x16_bf16 v[48:63], v[236:239], v[96:99], v[48:63]
	ds_read_b64 v[236:237], v227 offset:38688
	ds_read_b64 v[238:239], v227 offset:38704
	v_add_f32_e32 v197, v85, v197
	v_add_f32_e32 v197, v86, v197
	v_add_f32_e32 v197, v87, v197
	v_add_f32_e32 v197, v88, v197
	v_add_f32_e32 v197, v89, v197
	s_waitcnt lgkmcnt(10)
	v_mfma_f32_32x32x16_bf16 v[32:47], v[240:243], v[96:99], v[32:47]
	ds_read_b64 v[240:241], v227 offset:25664
	ds_read_b64 v[242:243], v227 offset:25680
	v_add_f32_e32 v197, v90, v197
	v_add_f32_e32 v197, v91, v197
	v_add_f32_e32 v197, v92, v197
	v_add_f32_e32 v197, v93, v197
	v_add_f32_e32 v197, v94, v197
	s_waitcnt lgkmcnt(10)
	v_mfma_f32_32x32x16_bf16 v[16:31], v[244:247], v[96:99], v[16:31]
	ds_read_b64 v[244:245], v227 offset:30016
	ds_read_b64 v[246:247], v227 offset:30032
	v_add_f32_e32 v197, v95, v197
	v_add_f32_e32 v15, v15, v197
	v_cvt_pk_bf16_f32 v80, v80, v81
	v_cvt_pk_bf16_f32 v81, v82, v83
	v_cvt_pk_bf16_f32 v82, v84, v85
	s_waitcnt lgkmcnt(10)
	v_mfma_f32_32x32x16_bf16 v[64:79], v[248:251], v[100:103], v[64:79]
	ds_read_b64 v[248:249], v227 offset:34368
	ds_read_b64 v[250:251], v227 offset:34384
	v_cvt_pk_bf16_f32 v83, v86, v87
	v_cvt_pk_bf16_f32 v84, v88, v89
	v_cvt_pk_bf16_f32 v85, v90, v91
	v_cvt_pk_bf16_f32 v86, v92, v93
	v_cvt_pk_bf16_f32 v87, v94, v95
	s_waitcnt lgkmcnt(10)
	v_mfma_f32_32x32x16_bf16 v[48:63], v[252:255], v[100:103], v[48:63]
	ds_read_b64 v[252:253], v227 offset:38720
	ds_read_b64 v[254:255], v227 offset:38736
	s_waitcnt lgkmcnt(10)
	v_mfma_f32_32x32x16_bf16 v[32:47], v[232:235], v[100:103], v[32:47]
	ds_read_b64 v[232:233], v227 offset:25696
	ds_read_b64 v[234:235], v227 offset:25712
	s_waitcnt lgkmcnt(10)
	v_mfma_f32_32x32x16_bf16 v[16:31], v[236:239], v[100:103], v[16:31]
	ds_read_b64 v[236:237], v227 offset:30048
	ds_read_b64 v[238:239], v227 offset:30064
	s_waitcnt lgkmcnt(10)
	v_mfma_f32_32x32x16_bf16 v[64:79], v[240:243], v[80:83], v[64:79]
	ds_read_b64 v[240:241], v227 offset:34400
	ds_read_b64 v[242:243], v227 offset:34416
	s_waitcnt lgkmcnt(10)
	v_mfma_f32_32x32x16_bf16 v[48:63], v[244:247], v[80:83], v[48:63]
	ds_read_b64 v[244:245], v227 offset:38752
	ds_read_b64 v[246:247], v227 offset:38768
	s_waitcnt lgkmcnt(10)
	v_mfma_f32_32x32x16_bf16 v[32:47], v[248:251], v[80:83], v[32:47]
	s_waitcnt lgkmcnt(8)
	v_mfma_f32_32x32x16_bf16 v[16:31], v[252:255], v[80:83], v[16:31]
	s_waitcnt lgkmcnt(6)
	v_mfma_f32_32x32x16_bf16 v[64:79], v[232:235], v[84:87], v[64:79]
	s_waitcnt lgkmcnt(4)
	v_mfma_f32_32x32x16_bf16 v[48:63], v[236:239], v[84:87], v[48:63]
	s_waitcnt lgkmcnt(2)
	v_mfma_f32_32x32x16_bf16 v[32:47], v[240:243], v[84:87], v[32:47]
	s_waitcnt lgkmcnt(0)
	v_mfma_f32_32x32x16_bf16 v[16:31], v[244:247], v[84:87], v[16:31]
	s_setprio 0

; #define ATT_SSTORE() do { \
;     *(uint4*)(ldsK) = rk0; *(uint4*)(ldsK + 16 * KLD) = rk1; *(uint4*)(ldsK + 32 * KLD) = rk2; *(uint4*)(ldsK + 48 * KLD) = rk3; \
;     if (DQK == 192) { *(uint4*)(ldsR) = rk4; *(uint4*)(ldsR + 32 * KLD) = rk5; } \
;     ATT_VST(0, rv0); ATT_VST(1, rv1); ATT_VST(2, rv2); ATT_VST(3, rv3); } while (0)
;     ...
;   ATT_GLOAD(rev ? nkt - 1 : 0);
;   for (int kt = 0; kt < nkt; kt++) {
;     __syncthreads();
;     ATT_SSTORE();
;     __syncthreads();
;     const int ktile = rev ? nkt - 1 - kt : kt;
;     const bool active = ktile < nkt_w;
;     f32x16 s[2];
;     if (active) {
.LBB0_656:
	s_waitcnt lgkmcnt(0)
	s_barrier
	s_waitcnt vmcnt(9)
	ds_write_b128 v176, v[132:135]
	s_waitcnt vmcnt(8)
	ds_write_b128 v176, v[136:139] offset:6400
	s_waitcnt vmcnt(7)
	ds_write_b128 v176, v[140:143] offset:12800
	s_waitcnt vmcnt(6)
	ds_write_b128 v176, v[144:147] offset:19200
	s_waitcnt vmcnt(5)
	ds_write_b128 v174, v[152:155] offset:256
	s_waitcnt vmcnt(4)
	ds_write_b128 v174, v[148:151] offset:13056
	v_mov_b32_e32 v132, s2
	v_cndmask_b32_e64 v132, v132, v192, s[8:9]
	v_add_u32_e32 v193, 0x6400, v178
	v_add_u32_e32 v194, 0x7500, v178
	v_add_u32_e32 v195, 0x8600, v178
	v_add_u32_e32 v196, 0x9700, v178
	v_cmp_lt_i32_e64 s[10:11], v132, v188
	s_waitcnt vmcnt(1)
	ds_write2_b64 v193, v[168:169], v[170:171] offset1:1
	ds_write2_b64 v194, v[156:157], v[158:159] offset1:1
	ds_write2_b64 v195, v[160:161], v[162:163] offset1:1
	s_waitcnt vmcnt(0)
	ds_write2_b64 v196, v[164:165], v[166:167] offset1:1
	s_waitcnt lgkmcnt(0)
	s_barrier
	v_add_u32_e32 v156, v132, v191
	v_ashrrev_i32_e32 v157, 31, v156
	v_lshlrev_b32_e32 v148, 6, v156
	v_lshlrev_b64 v[156:157], 14, v[156:157]
	v_lshl_add_u64 v[156:157], v[172:173], 0, v[156:157]
	v_lshl_add_u64 v[160:161], v[156:157], 0, v[0:1]
	s_movk_i32 s3, 0x1000
	v_add_co_u32_e32 v156, vcc, s3, v160
	v_or_b32_e32 v134, 16, v148
	s_nop 0
	v_addc_co_u32_e32 v157, vcc, 0, v161, vcc
	v_or_b32_e32 v150, 32, v148
	v_or_b32_e32 v142, 48, v148
	v_add_co_u32_e32 v162, vcc, 0x2000, v160
	v_ashrrev_i32_e32 v149, 31, v148
	v_ashrrev_i32_e32 v135, 31, v134
	v_ashrrev_i32_e32 v151, 31, v150
	v_ashrrev_i32_e32 v143, 31, v142
	v_addc_co_u32_e32 v163, vcc, 0, v161, vcc
	v_lshlrev_b64 v[132:133], 8, v[148:149]
	v_lshlrev_b64 v[134:135], 8, v[134:135]
	v_lshlrev_b64 v[140:141], 8, v[150:151]
	v_lshlrev_b64 v[142:143], 8, v[142:143]
	v_lshlrev_b64 v[148:149], 7, v[148:149]
	v_lshlrev_b64 v[150:151], 7, v[150:151]
	v_add_co_u32_e32 v164, vcc, 0x3000, v160
	v_lshl_add_u64 v[132:133], v[180:181], 0, v[132:133]
	v_lshl_add_u64 v[136:137], v[180:181], 0, v[134:135]
	v_lshl_add_u64 v[140:141], v[180:181], 0, v[140:141]
	v_lshl_add_u64 v[144:145], v[180:181], 0, v[142:143]
	v_lshl_add_u64 v[148:149], v[182:183], 0, v[148:149]
	v_lshl_add_u64 v[150:151], v[182:183], 0, v[150:151]
	v_addc_co_u32_e32 v165, vcc, 0, v161, vcc
	global_load_dwordx4 v[132:135], v[132:133], off
	s_nop 0
	global_load_dwordx4 v[136:139], v[136:137], off
	s_nop 0
	global_load_dwordx4 v[140:143], v[140:141], off
	s_nop 0
	global_load_dwordx4 v[144:147], v[144:145], off
	s_nop 0
	global_load_dwordx4 v[152:155], v[148:149], off
	s_nop 0
	global_load_dwordx4 v[148:151], v[150:151], off
	s_nop 0
	global_load_dwordx4 v[168:171], v[160:161], off
	s_nop 0
	global_load_dwordx4 v[156:159], v[156:157], off
	s_nop 0
	global_load_dwordx4 v[160:163], v[162:163], off
	s_nop 0
	global_load_dwordx4 v[164:167], v[164:165], off
	s_and_saveexec_b64 s[26:27], s[10:11]
	s_cbranch_execz .LBB0_655
; #define MFMA(a, b, c) __builtin_amdgcn_mfma_f32_32x32x16_bf16((a), (b), (c), 0, 0, 0)
;     ...
;       bf16x8 qx[(NQF > NQR) ? (NQF - NQR) : 1];
;       if (NQF > NQR) {
; #pragma unroll
;         for (int ks = NQR; ks < NQF; ks++) qx[ks - NQR] = *(const bf16x8*)(Qs + (w * 32 + r) * 72 + (ks - NQR) * 16 + h * 8);
;       }
;       __builtin_amdgcn_s_setprio(1);
; #pragma unroll
;       for (int ks = 0; ks < NQF; ks++) {
; #pragma unroll
;         for (int mt = 0; mt < 2; mt++) {
;           const bf16x8 kf = *(const bf16x8*)(Ks + (mt * 32 + r) * KLD + ks * 16 + h * 8);
;           s[mt] = MFMA(kf, (ks < NQR) ? qf[ks < NQR ? ks : 0] : qx[ks >= NQR ? ks - NQR : 0], (ks == 0) ? zero16 : s[mt]);
;         }
;       }
;       __builtin_amdgcn_s_setprio(0);
;     }
;     __builtin_amdgcn_sched_barrier(0);
;     if (kt + 1 < nkt) ATT_GLOAD(rev ? ktile - 1 : ktile + 1);
;     __builtin_amdgcn_sched_barrier(0);
;     if (active) {
;       float mx = s[0][0];
; #pragma unroll
;       for (int mt = 0; mt < 2; mt++)
; #pragma unroll
;         for (int i = 0; i < 16; i++) mx = fmaxf(mx, s[mt][i]);
;       mx = fmaxf(mx, __shfl_xor(mx, 32));
;       if (__builtin_amdgcn_ballot_w64(mx > m_run + 8.f) != 0ull) {
;         const float m_new = fmaxf(m_run, mx);
;         const float alpha = __builtin_amdgcn_exp2f(m_run - m_new);
;         m_run = m_new;
;         l_run *= alpha;
; #pragma unroll
;         for (int mc = 0; mc < 4; mc++)
; #pragma unroll
;           for (int i = 0; i < 16; i++) o[mc][i] *= alpha;
;       }
	v_add_u32_e32 v227, v14, v189
	ds_read_b128 v[232:235], v227
	ds_read_b128 v[236:239], v227 offset:12800
	ds_read_b128 v[240:243], v227 offset:32
	ds_read_b128 v[244:247], v227 offset:12832
	ds_read_b128 v[248:251], v227 offset:64
	ds_read_b128 v[252:255], v227 offset:12864
	s_setprio 1
	s_waitcnt lgkmcnt(5)
	v_mfma_f32_32x32x16_bf16 v[96:111], v[232:235], v[128:131], 0
	ds_read_b128 v[232:235], v227 offset:96
	s_waitcnt lgkmcnt(5)
	v_mfma_f32_32x32x16_bf16 v[80:95], v[236:239], v[128:131], 0
	ds_read_b128 v[236:239], v227 offset:12896
	s_waitcnt lgkmcnt(5)
	v_mfma_f32_32x32x16_bf16 v[96:111], v[240:243], v[124:127], v[96:111]
	ds_read_b128 v[240:243], v227 offset:128
	s_waitcnt lgkmcnt(5)
	v_mfma_f32_32x32x16_bf16 v[80:95], v[244:247], v[124:127], v[80:95]
	ds_read_b128 v[244:247], v227 offset:12928
	s_waitcnt lgkmcnt(5)
	v_mfma_f32_32x32x16_bf16 v[96:111], v[248:251], v[120:123], v[96:111]
	ds_read_b128 v[248:251], v227 offset:160
	s_waitcnt lgkmcnt(5)
	v_mfma_f32_32x32x16_bf16 v[80:95], v[252:255], v[120:123], v[80:95]
	ds_read_b128 v[252:255], v227 offset:12960
	s_waitcnt lgkmcnt(5)
	v_mfma_f32_32x32x16_bf16 v[96:111], v[232:235], v[116:119], v[96:111]
	ds_read_b128 v[232:235], v227 offset:192
	s_waitcnt lgkmcnt(5)
	v_mfma_f32_32x32x16_bf16 v[80:95], v[236:239], v[116:119], v[80:95]
	ds_read_b128 v[236:239], v227 offset:12992
	s_waitcnt lgkmcnt(5)
	v_mfma_f32_32x32x16_bf16 v[96:111], v[240:243], v[112:115], v[96:111]
	ds_read_b128 v[240:243], v227 offset:224
	s_waitcnt lgkmcnt(5)
	v_mfma_f32_32x32x16_bf16 v[80:95], v[244:247], v[112:115], v[80:95]
	ds_read_b128 v[244:247], v227 offset:13024
	s_waitcnt lgkmcnt(5)
	v_mfma_f32_32x32x16_bf16 v[96:111], v[248:251], v[10:13], v[96:111]
	ds_read_b128 v[248:251], v227 offset:256
	s_waitcnt lgkmcnt(5)
	v_mfma_f32_32x32x16_bf16 v[80:95], v[252:255], v[10:13], v[80:95]
	ds_read_b128 v[252:255], v227 offset:13056
	s_waitcnt lgkmcnt(5)
	v_mfma_f32_32x32x16_bf16 v[96:111], v[232:235], v[6:9], v[96:111]
	ds_read_b128 v[232:235], v227 offset:288
	s_waitcnt lgkmcnt(5)
	v_mfma_f32_32x32x16_bf16 v[80:95], v[236:239], v[6:9], v[80:95]
	ds_read_b128 v[236:239], v227 offset:13088
	s_waitcnt lgkmcnt(5)
	v_mfma_f32_32x32x16_bf16 v[96:111], v[240:243], v[2:5], v[96:111]
	ds_read_b128 v[240:243], v227 offset:320
	s_waitcnt lgkmcnt(5)
	v_mfma_f32_32x32x16_bf16 v[80:95], v[244:247], v[2:5], v[80:95]
	ds_read_b128 v[244:247], v227 offset:13120
	s_waitcnt lgkmcnt(5)
	v_mfma_f32_32x32x16_bf16 v[96:111], v[248:251], v[214:217], v[96:111]
	ds_read_b128 v[248:251], v227 offset:352
	s_waitcnt lgkmcnt(5)
	v_mfma_f32_32x32x16_bf16 v[80:95], v[252:255], v[214:217], v[80:95]
	ds_read_b128 v[252:255], v227 offset:13152
	s_waitcnt lgkmcnt(5)
	v_mfma_f32_32x32x16_bf16 v[96:111], v[232:235], v[218:221], v[96:111]
	s_waitcnt lgkmcnt(4)
	v_mfma_f32_32x32x16_bf16 v[80:95], v[236:239], v[218:221], v[80:95]
	s_waitcnt lgkmcnt(3)
	v_mfma_f32_32x32x16_bf16 v[96:111], v[240:243], v[222:225], v[96:111]
	s_waitcnt lgkmcnt(2)
	v_mfma_f32_32x32x16_bf16 v[80:95], v[244:247], v[222:225], v[80:95]
	s_waitcnt lgkmcnt(1)
	v_mfma_f32_32x32x16_bf16 v[96:111], v[248:251], v[228:231], v[96:111]
	s_waitcnt lgkmcnt(0)
	v_mfma_f32_32x32x16_bf16 v[80:95], v[252:255], v[228:231], v[80:95]
	s_setprio 0
	v_add_u32_e32 v227, v175, v177
	ds_read_b64 v[232:233], v227 offset:25600
	ds_read_b64 v[234:235], v227 offset:25616
	ds_read_b64 v[236:237], v227 offset:29952
	ds_read_b64 v[238:239], v227 offset:29968
	ds_read_b64 v[240:241], v227 offset:34304
	ds_read_b64 v[242:243], v227 offset:34320
	ds_read_b64 v[244:245], v227 offset:38656
	ds_read_b64 v[246:247], v227 offset:38672
	ds_read_b64 v[248:249], v227 offset:25632
	ds_read_b64 v[250:251], v227 offset:25648
	ds_read_b64 v[252:253], v227 offset:29984
	ds_read_b64 v[254:255], v227 offset:30000
	v_max_f32_e32 v197, v97, v97
	v_max_f32_e32 v198, v96, v96
	v_max_f32_e32 v197, v198, v197
	v_max3_f32 v197, v197, v98, v99
	v_max3_f32 v197, v197, v100, v101
	v_max3_f32 v197, v197, v102, v103
	v_max3_f32 v197, v197, v104, v105
	v_max3_f32 v197, v197, v106, v107
	v_max3_f32 v197, v197, v108, v109
	v_max3_f32 v197, v197, v110, v111
	v_max3_f32 v197, v197, v80, v81
	v_max3_f32 v197, v197, v82, v83
	v_max3_f32 v197, v197, v84, v85
	v_max3_f32 v197, v197, v86, v87
	v_max3_f32 v197, v197, v88, v89
	v_max3_f32 v197, v197, v90, v91
	v_max3_f32 v197, v197, v92, v93
	v_max3_f32 v197, v197, v94, v95
	v_mov_b32_e32 v198, v197
	s_nop 1
	v_permlane32_swap_b32_e32 v197, v198
	v_max_f32_e32 v197, v197, v198
	v_add_f32_e32 v198, 0x41000000, v179
	v_cmp_gt_f32_e32 vcc, v197, v198
	s_cbranch_vccz .LBB0_654
	v_max_f32_e32 v197, v197, v197
	v_max_f32_e32 v198, v179, v179
	v_max_f32_e32 v197, v198, v197
	v_sub_f32_e32 v179, v179, v197
	v_exp_f32_e32 v198, v179
	v_mov_b32_e32 v179, v197
	v_pk_mul_f32 v[78:79], v[78:79], v[198:199] op_sel_hi:[1,0]
	v_pk_mul_f32 v[76:77], v[76:77], v[198:199] op_sel_hi:[1,0]
	v_pk_mul_f32 v[74:75], v[74:75], v[198:199] op_sel_hi:[1,0]
	v_pk_mul_f32 v[72:73], v[72:73], v[198:199] op_sel_hi:[1,0]
	v_pk_mul_f32 v[70:71], v[70:71], v[198:199] op_sel_hi:[1,0]
	v_pk_mul_f32 v[68:69], v[68:69], v[198:199] op_sel_hi:[1,0]
	v_pk_mul_f32 v[66:67], v[66:67], v[198:199] op_sel_hi:[1,0]
	v_pk_mul_f32 v[64:65], v[64:65], v[198:199] op_sel_hi:[1,0]
	v_pk_mul_f32 v[62:63], v[62:63], v[198:199] op_sel_hi:[1,0]
	v_pk_mul_f32 v[60:61], v[60:61], v[198:199] op_sel_hi:[1,0]
	v_pk_mul_f32 v[58:59], v[58:59], v[198:199] op_sel_hi:[1,0]
	v_pk_mul_f32 v[56:57], v[56:57], v[198:199] op_sel_hi:[1,0]
	v_pk_mul_f32 v[54:55], v[54:55], v[198:199] op_sel_hi:[1,0]
	v_pk_mul_f32 v[52:53], v[52:53], v[198:199] op_sel_hi:[1,0]
	v_pk_mul_f32 v[50:51], v[50:51], v[198:199] op_sel_hi:[1,0]
	v_pk_mul_f32 v[48:49], v[48:49], v[198:199] op_sel_hi:[1,0]
	v_pk_mul_f32 v[46:47], v[46:47], v[198:199] op_sel_hi:[1,0]
	v_pk_mul_f32 v[44:45], v[44:45], v[198:199] op_sel_hi:[1,0]
	v_pk_mul_f32 v[42:43], v[42:43], v[198:199] op_sel_hi:[1,0]
	v_pk_mul_f32 v[40:41], v[40:41], v[198:199] op_sel_hi:[1,0]
	v_pk_mul_f32 v[38:39], v[38:39], v[198:199] op_sel_hi:[1,0]
	v_pk_mul_f32 v[36:37], v[36:37], v[198:199] op_sel_hi:[1,0]
	v_pk_mul_f32 v[34:35], v[34:35], v[198:199] op_sel_hi:[1,0]
	v_pk_mul_f32 v[32:33], v[32:33], v[198:199] op_sel_hi:[1,0]
	v_pk_mul_f32 v[30:31], v[30:31], v[198:199] op_sel_hi:[1,0]
	v_pk_mul_f32 v[28:29], v[28:29], v[198:199] op_sel_hi:[1,0]
	v_pk_mul_f32 v[26:27], v[26:27], v[198:199] op_sel_hi:[1,0]
	v_pk_mul_f32 v[24:25], v[24:25], v[198:199] op_sel_hi:[1,0]
	v_pk_mul_f32 v[22:23], v[22:23], v[198:199] op_sel_hi:[1,0]
	v_pk_mul_f32 v[20:21], v[20:21], v[198:199] op_sel_hi:[1,0]
	v_pk_mul_f32 v[18:19], v[18:19], v[198:199] op_sel_hi:[1,0]
	v_pk_mul_f32 v[16:17], v[16:17], v[198:199] op_sel_hi:[1,0]
	v_mul_f32_e32 v15, v15, v198
	s_branch .LBB0_654
